# P1 sliver GEMM: per-block operand double-buffered in registers (next-next block's loads in flight during the reduction), on top of v98
# speedup vs baseline: 1.0013x; 1.0013x over previous
.LBB0_237:
	s_waitcnt vmcnt(0)
	s_waitcnt vmcnt(0)
	v_and_b32_e32 v148, 63, v154
	v_lshrrev_b32_e32 v149, 6, v154
	v_and_b32_e32 v150, 31, v148
	v_lshrrev_b32_e32 v151, 5, v148
	v_lshlrev_b32_e32 v152, 6, v151
	v_lshl_or_b32 v152, v149, 9, v152
	s_add_u32 s50, s28, 0x4100000
	s_addc_u32 s51, s29, 0
	s_add_u32 s52, s28, 0x17400000
	s_addc_u32 s53, s29, 0
	s_add_u32 s54, s28, 0x7000000
	s_addc_u32 s55, s29, 0
	v_lshlrev_b32_e32 v153, 4, v148
	v_lshl_add_u32 v153, v149, 12, v153
	v_lshrrev_b32_e32 v157, 1, v149
	v_lshlrev_b32_e32 v156, 4, v148
	v_lshl_add_u32 v156, v157, 10, v156
	v_and_b32_e32 v159, 1, v149
	v_lshl_add_u32 v156, v159, 3, v156
	v_lshlrev_b32_e32 v158, 1, v159
	v_lshl_add_u32 v158, v157, 3, v158
	v_lshl_add_u32 v158, v151, 2, v158
	s_mov_b32 s58, 0
	s_sub_i32 s48, s2, 0xab
	s_cmp_lt_u32 s2, 0xab
	s_cselect_b32 s59, 1, 0
	s_movk_i32 s60, 0x55
	s_cselect_b32 s60, 0xab, s60
	s_movk_i32 s61, 0x100
	s_cselect_b32 s61, 0x201, s61
	s_cselect_b32 s48, s2, s48
	s_mov_b32 s46, s48
	s_lshl_b32 s56, s46, 5
	v_add_u32_e32 v144, s56, v150
	v_lshl_add_u32 v144, v144, 12, v152
	s_add_i32 s46, s46, s60
	s_lshl_b32 s56, s46, 5
	v_add_u32_e32 v145, s56, v150
	v_lshl_add_u32 v145, v145, 12, v152
	s_add_i32 s46, s46, s60
	s_lshl_b32 s56, s46, 5
	v_add_u32_e32 v248, s56, v150
	v_lshl_add_u32 v248, v248, 12, v152
	s_add_i32 s46, s46, s60
	s_lshl_b32 s56, s46, 5
	v_add_u32_e32 v249, s56, v150
	v_lshl_add_u32 v249, v249, 12, v152
	s_add_i32 s46, s46, s60
	s_lshl_b32 s56, s60, 1
	s_add_i32 s56, s56, s60
	s_add_i32 s57, s48, s56
	s_movk_i32 s56, 0x4000
	s_cmp_eq_u32 s59, 1
	s_cselect_b32 s56, 0x2000, s56
	v_add_u32_e32 v146, s56, v150
	v_lshl_add_u32 v146, v146, 12, v152
	s_mov_b32 s46, s48
	s_cmp_eq_u32 s59, 1
	s_cbranch_scc0 .Lsl_meta
	global_load_dwordx4 v[64:67], v146, s[50:51]
	global_load_dwordx4 v[68:71], v146, s[50:51] offset:16
	global_load_dwordx4 v[72:75], v146, s[50:51] offset:32
	global_load_dwordx4 v[76:79], v146, s[50:51] offset:48
	global_load_dwordx4 v[80:83], v146, s[50:51] offset:128
	global_load_dwordx4 v[84:87], v146, s[50:51] offset:144
	global_load_dwordx4 v[88:91], v146, s[50:51] offset:160
	global_load_dwordx4 v[92:95], v146, s[50:51] offset:176
	global_load_dwordx4 v[96:99], v146, s[50:51] offset:256
	global_load_dwordx4 v[100:103], v146, s[50:51] offset:272
	global_load_dwordx4 v[104:107], v146, s[50:51] offset:288
	global_load_dwordx4 v[108:111], v146, s[50:51] offset:304
	global_load_dwordx4 v[112:115], v146, s[50:51] offset:384
	global_load_dwordx4 v[116:119], v146, s[50:51] offset:400
	global_load_dwordx4 v[120:123], v146, s[50:51] offset:416
	global_load_dwordx4 v[124:127], v146, s[50:51] offset:432
	global_load_dwordx4 v[0:3], v144, s[28:29]
	global_load_dwordx4 v[4:7], v144, s[28:29] offset:16
	global_load_dwordx4 v[8:11], v144, s[28:29] offset:32
	global_load_dwordx4 v[12:15], v144, s[28:29] offset:48
	global_load_dwordx4 v[16:19], v144, s[28:29] offset:128
	global_load_dwordx4 v[20:23], v144, s[28:29] offset:144
	global_load_dwordx4 v[24:27], v144, s[28:29] offset:160
	global_load_dwordx4 v[28:31], v144, s[28:29] offset:176
	global_load_dwordx4 v[32:35], v144, s[28:29] offset:256
	global_load_dwordx4 v[36:39], v144, s[28:29] offset:272
	global_load_dwordx4 v[40:43], v144, s[28:29] offset:288
	global_load_dwordx4 v[44:47], v144, s[28:29] offset:304
	global_load_dwordx4 v[48:51], v144, s[28:29] offset:384
	global_load_dwordx4 v[52:55], v144, s[28:29] offset:400
	global_load_dwordx4 v[56:59], v144, s[28:29] offset:416
	global_load_dwordx4 v[60:63], v144, s[28:29] offset:432
	global_load_dwordx4 v[180:183], v145, s[28:29]
	global_load_dwordx4 v[184:187], v145, s[28:29] offset:16
	global_load_dwordx4 v[188:191], v145, s[28:29] offset:32
	global_load_dwordx4 v[192:195], v145, s[28:29] offset:48
	global_load_dwordx4 v[196:199], v145, s[28:29] offset:128
	global_load_dwordx4 v[200:203], v145, s[28:29] offset:144
	global_load_dwordx4 v[204:207], v145, s[28:29] offset:160
	global_load_dwordx4 v[208:211], v145, s[28:29] offset:176
	global_load_dwordx4 v[212:215], v145, s[28:29] offset:256
	global_load_dwordx4 v[216:219], v145, s[28:29] offset:272
	global_load_dwordx4 v[220:223], v145, s[28:29] offset:288
	global_load_dwordx4 v[224:227], v145, s[28:29] offset:304
	global_load_dwordx4 v[228:231], v145, s[28:29] offset:384
	global_load_dwordx4 v[232:235], v145, s[28:29] offset:400
	global_load_dwordx4 v[236:239], v145, s[28:29] offset:416
	global_load_dwordx4 v[240:243], v145, s[28:29] offset:432
	s_waitcnt vmcnt(28)
	v_mfma_f32_32x32x16_bf16 v[128:143], v[64:67], v[0:3], 0
	v_mfma_f32_32x32x16_bf16 v[128:143], v[68:71], v[4:7], v[128:143]
	v_mfma_f32_32x32x16_bf16 v[128:143], v[72:75], v[8:11], v[128:143]
	v_mfma_f32_32x32x16_bf16 v[128:143], v[76:79], v[12:15], v[128:143]
	s_waitcnt vmcnt(24)
	v_mfma_f32_32x32x16_bf16 v[128:143], v[80:83], v[16:19], v[128:143]
	v_mfma_f32_32x32x16_bf16 v[128:143], v[84:87], v[20:23], v[128:143]
	v_mfma_f32_32x32x16_bf16 v[128:143], v[88:91], v[24:27], v[128:143]
	v_mfma_f32_32x32x16_bf16 v[128:143], v[92:95], v[28:31], v[128:143]
	s_waitcnt vmcnt(20)
	v_mfma_f32_32x32x16_bf16 v[128:143], v[96:99], v[32:35], v[128:143]
	v_mfma_f32_32x32x16_bf16 v[128:143], v[100:103], v[36:39], v[128:143]
	v_mfma_f32_32x32x16_bf16 v[128:143], v[104:107], v[40:43], v[128:143]
	v_mfma_f32_32x32x16_bf16 v[128:143], v[108:111], v[44:47], v[128:143]
	s_waitcnt vmcnt(16)
	v_mfma_f32_32x32x16_bf16 v[128:143], v[112:115], v[48:51], v[128:143]
	v_mfma_f32_32x32x16_bf16 v[128:143], v[116:119], v[52:55], v[128:143]
	v_mfma_f32_32x32x16_bf16 v[128:143], v[120:123], v[56:59], v[128:143]
	v_mfma_f32_32x32x16_bf16 v[128:143], v[124:127], v[60:63], v[128:143]
	global_load_dwordx4 v[0:3], v248, s[28:29]
	global_load_dwordx4 v[4:7], v248, s[28:29] offset:16
	global_load_dwordx4 v[8:11], v248, s[28:29] offset:32
	global_load_dwordx4 v[12:15], v248, s[28:29] offset:48
	global_load_dwordx4 v[16:19], v248, s[28:29] offset:128
	global_load_dwordx4 v[20:23], v248, s[28:29] offset:144
	global_load_dwordx4 v[24:27], v248, s[28:29] offset:160
	global_load_dwordx4 v[28:31], v248, s[28:29] offset:176
	global_load_dwordx4 v[32:35], v248, s[28:29] offset:256
	global_load_dwordx4 v[36:39], v248, s[28:29] offset:272
	global_load_dwordx4 v[40:43], v248, s[28:29] offset:288
	global_load_dwordx4 v[44:47], v248, s[28:29] offset:304
	global_load_dwordx4 v[48:51], v248, s[28:29] offset:384
	global_load_dwordx4 v[52:55], v248, s[28:29] offset:400
	global_load_dwordx4 v[56:59], v248, s[28:29] offset:416
	global_load_dwordx4 v[60:63], v248, s[28:29] offset:432
	s_nop 15
	v_add_u32_e32 v160, s58, v153
	ds_write_b128 v160, v[128:131]
	ds_write_b128 v160, v[132:135] offset:1024
	ds_write_b128 v160, v[136:139] offset:2048
	ds_write_b128 v160, v[140:143] offset:3072
	s_waitcnt lgkmcnt(0)
	s_barrier
	v_add_u32_e32 v161, s58, v156
	ds_read_b64 v[162:163], v161
	ds_read_b64 v[164:165], v161 offset:4096
	ds_read_b64 v[166:167], v161 offset:8192
	ds_read_b64 v[168:169], v161 offset:12288
	ds_read_b64 v[170:171], v161 offset:16384
	ds_read_b64 v[172:173], v161 offset:20480
	ds_read_b64 v[174:175], v161 offset:24576
	ds_read_b64 v[176:177], v161 offset:28672
	s_xor_b32 s58, s58, 0x8000
	s_waitcnt lgkmcnt(0)
	v_add_f32_e32 v162, v162, v164
	v_add_f32_e32 v163, v163, v165
	v_add_f32_e32 v162, v162, v166
	v_add_f32_e32 v163, v163, v167
	v_add_f32_e32 v162, v162, v168
	v_add_f32_e32 v163, v163, v169
	v_add_f32_e32 v162, v162, v170
	v_add_f32_e32 v163, v163, v171
	v_add_f32_e32 v162, v162, v172
	v_add_f32_e32 v163, v163, v173
	v_add_f32_e32 v162, v162, v174
	v_add_f32_e32 v163, v163, v175
	v_add_f32_e32 v162, v162, v176
	v_add_f32_e32 v163, v163, v177
	s_lshl_b32 s56, s46, 5
	v_add_u32_e32 v164, s56, v150
	v_lshlrev_b32_e32 v164, 7, v164
	v_lshl_add_u32 v164, v158, 2, v164
	global_store_dwordx2 v164, v[162:163], s[52:53]
	s_add_i32 s46, s46, s60
	s_waitcnt vmcnt(29)
	v_mfma_f32_32x32x16_bf16 v[128:143], v[64:67], v[180:183], 0
	v_mfma_f32_32x32x16_bf16 v[128:143], v[68:71], v[184:187], v[128:143]
	v_mfma_f32_32x32x16_bf16 v[128:143], v[72:75], v[188:191], v[128:143]
	v_mfma_f32_32x32x16_bf16 v[128:143], v[76:79], v[192:195], v[128:143]
	s_waitcnt vmcnt(25)
	v_mfma_f32_32x32x16_bf16 v[128:143], v[80:83], v[196:199], v[128:143]
	v_mfma_f32_32x32x16_bf16 v[128:143], v[84:87], v[200:203], v[128:143]
	v_mfma_f32_32x32x16_bf16 v[128:143], v[88:91], v[204:207], v[128:143]
	v_mfma_f32_32x32x16_bf16 v[128:143], v[92:95], v[208:211], v[128:143]
	s_waitcnt vmcnt(21)
	v_mfma_f32_32x32x16_bf16 v[128:143], v[96:99], v[212:215], v[128:143]
	v_mfma_f32_32x32x16_bf16 v[128:143], v[100:103], v[216:219], v[128:143]
	v_mfma_f32_32x32x16_bf16 v[128:143], v[104:107], v[220:223], v[128:143]
	v_mfma_f32_32x32x16_bf16 v[128:143], v[108:111], v[224:227], v[128:143]
	s_waitcnt vmcnt(17)
	v_mfma_f32_32x32x16_bf16 v[128:143], v[112:115], v[228:231], v[128:143]
	v_mfma_f32_32x32x16_bf16 v[128:143], v[116:119], v[232:235], v[128:143]
	v_mfma_f32_32x32x16_bf16 v[128:143], v[120:123], v[236:239], v[128:143]
	v_mfma_f32_32x32x16_bf16 v[128:143], v[124:127], v[240:243], v[128:143]
	s_cmp_lt_u32 s57, s61
	s_cbranch_scc0 .Lsl_no3_n
	global_load_dwordx4 v[180:183], v249, s[28:29]
	global_load_dwordx4 v[184:187], v249, s[28:29] offset:16
	global_load_dwordx4 v[188:191], v249, s[28:29] offset:32
	global_load_dwordx4 v[192:195], v249, s[28:29] offset:48
	global_load_dwordx4 v[196:199], v249, s[28:29] offset:128
	global_load_dwordx4 v[200:203], v249, s[28:29] offset:144
	global_load_dwordx4 v[204:207], v249, s[28:29] offset:160
	global_load_dwordx4 v[208:211], v249, s[28:29] offset:176
	global_load_dwordx4 v[212:215], v249, s[28:29] offset:256
	global_load_dwordx4 v[216:219], v249, s[28:29] offset:272
	global_load_dwordx4 v[220:223], v249, s[28:29] offset:288
	global_load_dwordx4 v[224:227], v249, s[28:29] offset:304
	global_load_dwordx4 v[228:231], v249, s[28:29] offset:384
	global_load_dwordx4 v[232:235], v249, s[28:29] offset:400
	global_load_dwordx4 v[236:239], v249, s[28:29] offset:416
	global_load_dwordx4 v[240:243], v249, s[28:29] offset:432
.Lsl_no3_n:
	s_nop 15
	v_add_u32_e32 v160, s58, v153
	ds_write_b128 v160, v[128:131]
	ds_write_b128 v160, v[132:135] offset:1024
	ds_write_b128 v160, v[136:139] offset:2048
	ds_write_b128 v160, v[140:143] offset:3072
	s_waitcnt lgkmcnt(0)
	s_barrier
	v_add_u32_e32 v161, s58, v156
	ds_read_b64 v[162:163], v161
	ds_read_b64 v[164:165], v161 offset:4096
	ds_read_b64 v[166:167], v161 offset:8192
	ds_read_b64 v[168:169], v161 offset:12288
	ds_read_b64 v[170:171], v161 offset:16384
	ds_read_b64 v[172:173], v161 offset:20480
	ds_read_b64 v[174:175], v161 offset:24576
	ds_read_b64 v[176:177], v161 offset:28672
	s_xor_b32 s58, s58, 0x8000
	s_waitcnt lgkmcnt(0)
	v_add_f32_e32 v162, v162, v164
	v_add_f32_e32 v163, v163, v165
	v_add_f32_e32 v162, v162, v166
	v_add_f32_e32 v163, v163, v167
	v_add_f32_e32 v162, v162, v168
	v_add_f32_e32 v163, v163, v169
	v_add_f32_e32 v162, v162, v170
	v_add_f32_e32 v163, v163, v171
	v_add_f32_e32 v162, v162, v172
	v_add_f32_e32 v163, v163, v173
	v_add_f32_e32 v162, v162, v174
	v_add_f32_e32 v163, v163, v175
	v_add_f32_e32 v162, v162, v176
	v_add_f32_e32 v163, v163, v177
	s_lshl_b32 s56, s46, 5
	v_add_u32_e32 v164, s56, v150
	v_lshlrev_b32_e32 v164, 7, v164
	v_lshl_add_u32 v164, v158, 2, v164
	global_store_dwordx2 v164, v[162:163], s[52:53]
	s_add_i32 s46, s46, s60
	s_waitcnt vmcnt(14)
	v_mfma_f32_32x32x16_bf16 v[128:143], v[64:67], v[0:3], 0
	v_mfma_f32_32x32x16_bf16 v[128:143], v[68:71], v[4:7], v[128:143]
	v_mfma_f32_32x32x16_bf16 v[128:143], v[72:75], v[8:11], v[128:143]
	v_mfma_f32_32x32x16_bf16 v[128:143], v[76:79], v[12:15], v[128:143]
	s_waitcnt vmcnt(10)
	v_mfma_f32_32x32x16_bf16 v[128:143], v[80:83], v[16:19], v[128:143]
	v_mfma_f32_32x32x16_bf16 v[128:143], v[84:87], v[20:23], v[128:143]
	v_mfma_f32_32x32x16_bf16 v[128:143], v[88:91], v[24:27], v[128:143]
	v_mfma_f32_32x32x16_bf16 v[128:143], v[92:95], v[28:31], v[128:143]
	s_waitcnt vmcnt(6)
	v_mfma_f32_32x32x16_bf16 v[128:143], v[96:99], v[32:35], v[128:143]
	v_mfma_f32_32x32x16_bf16 v[128:143], v[100:103], v[36:39], v[128:143]
	v_mfma_f32_32x32x16_bf16 v[128:143], v[104:107], v[40:43], v[128:143]
	v_mfma_f32_32x32x16_bf16 v[128:143], v[108:111], v[44:47], v[128:143]
	s_waitcnt vmcnt(2)
	v_mfma_f32_32x32x16_bf16 v[128:143], v[112:115], v[48:51], v[128:143]
	v_mfma_f32_32x32x16_bf16 v[128:143], v[116:119], v[52:55], v[128:143]
	v_mfma_f32_32x32x16_bf16 v[128:143], v[120:123], v[56:59], v[128:143]
	v_mfma_f32_32x32x16_bf16 v[128:143], v[124:127], v[60:63], v[128:143]
	s_nop 15
	v_add_u32_e32 v160, s58, v153
	ds_write_b128 v160, v[128:131]
	ds_write_b128 v160, v[132:135] offset:1024
	ds_write_b128 v160, v[136:139] offset:2048
	ds_write_b128 v160, v[140:143] offset:3072
	s_waitcnt lgkmcnt(0)
	s_barrier
	v_add_u32_e32 v161, s58, v156
	ds_read_b64 v[162:163], v161
	ds_read_b64 v[164:165], v161 offset:4096
	ds_read_b64 v[166:167], v161 offset:8192
	ds_read_b64 v[168:169], v161 offset:12288
	ds_read_b64 v[170:171], v161 offset:16384
	ds_read_b64 v[172:173], v161 offset:20480
	ds_read_b64 v[174:175], v161 offset:24576
	ds_read_b64 v[176:177], v161 offset:28672
	s_xor_b32 s58, s58, 0x8000
	s_waitcnt lgkmcnt(0)
	v_add_f32_e32 v162, v162, v164
	v_add_f32_e32 v163, v163, v165
	v_add_f32_e32 v162, v162, v166
	v_add_f32_e32 v163, v163, v167
	v_add_f32_e32 v162, v162, v168
	v_add_f32_e32 v163, v163, v169
	v_add_f32_e32 v162, v162, v170
	v_add_f32_e32 v163, v163, v171
	v_add_f32_e32 v162, v162, v172
	v_add_f32_e32 v163, v163, v173
	v_add_f32_e32 v162, v162, v174
	v_add_f32_e32 v163, v163, v175
	v_add_f32_e32 v162, v162, v176
	v_add_f32_e32 v163, v163, v177
	s_lshl_b32 s56, s46, 5
	v_add_u32_e32 v164, s56, v150
	v_lshlrev_b32_e32 v164, 7, v164
	v_lshl_add_u32 v164, v158, 2, v164
	global_store_dwordx2 v164, v[162:163], s[52:53]
	s_add_i32 s46, s46, s60
	s_cmp_lt_u32 s57, s61
	s_cbranch_scc0 .Lsl_done
	s_waitcnt vmcnt(14)
	v_mfma_f32_32x32x16_bf16 v[128:143], v[64:67], v[180:183], 0
	v_mfma_f32_32x32x16_bf16 v[128:143], v[68:71], v[184:187], v[128:143]
	v_mfma_f32_32x32x16_bf16 v[128:143], v[72:75], v[188:191], v[128:143]
	v_mfma_f32_32x32x16_bf16 v[128:143], v[76:79], v[192:195], v[128:143]
	s_waitcnt vmcnt(10)
	v_mfma_f32_32x32x16_bf16 v[128:143], v[80:83], v[196:199], v[128:143]
	v_mfma_f32_32x32x16_bf16 v[128:143], v[84:87], v[200:203], v[128:143]
	v_mfma_f32_32x32x16_bf16 v[128:143], v[88:91], v[204:207], v[128:143]
	v_mfma_f32_32x32x16_bf16 v[128:143], v[92:95], v[208:211], v[128:143]
	s_waitcnt vmcnt(6)
	v_mfma_f32_32x32x16_bf16 v[128:143], v[96:99], v[212:215], v[128:143]
	v_mfma_f32_32x32x16_bf16 v[128:143], v[100:103], v[216:219], v[128:143]
	v_mfma_f32_32x32x16_bf16 v[128:143], v[104:107], v[220:223], v[128:143]
	v_mfma_f32_32x32x16_bf16 v[128:143], v[108:111], v[224:227], v[128:143]
	s_waitcnt vmcnt(2)
	v_mfma_f32_32x32x16_bf16 v[128:143], v[112:115], v[228:231], v[128:143]
	v_mfma_f32_32x32x16_bf16 v[128:143], v[116:119], v[232:235], v[128:143]
	v_mfma_f32_32x32x16_bf16 v[128:143], v[120:123], v[236:239], v[128:143]
	v_mfma_f32_32x32x16_bf16 v[128:143], v[124:127], v[240:243], v[128:143]
	s_nop 15
	v_add_u32_e32 v160, s58, v153
	ds_write_b128 v160, v[128:131]
	ds_write_b128 v160, v[132:135] offset:1024
	ds_write_b128 v160, v[136:139] offset:2048
	ds_write_b128 v160, v[140:143] offset:3072
	s_waitcnt lgkmcnt(0)
	s_barrier
	v_add_u32_e32 v161, s58, v156
	ds_read_b64 v[162:163], v161
	ds_read_b64 v[164:165], v161 offset:4096
	ds_read_b64 v[166:167], v161 offset:8192
	ds_read_b64 v[168:169], v161 offset:12288
	ds_read_b64 v[170:171], v161 offset:16384
	ds_read_b64 v[172:173], v161 offset:20480
	ds_read_b64 v[174:175], v161 offset:24576
	ds_read_b64 v[176:177], v161 offset:28672
	s_xor_b32 s58, s58, 0x8000
	s_waitcnt lgkmcnt(0)
	v_add_f32_e32 v162, v162, v164
	v_add_f32_e32 v163, v163, v165
	v_add_f32_e32 v162, v162, v166
	v_add_f32_e32 v163, v163, v167
	v_add_f32_e32 v162, v162, v168
	v_add_f32_e32 v163, v163, v169
	v_add_f32_e32 v162, v162, v170
	v_add_f32_e32 v163, v163, v171
	v_add_f32_e32 v162, v162, v172
	v_add_f32_e32 v163, v163, v173
	v_add_f32_e32 v162, v162, v174
	v_add_f32_e32 v163, v163, v175
	v_add_f32_e32 v162, v162, v176
	v_add_f32_e32 v163, v163, v177
	s_lshl_b32 s56, s46, 5
	v_add_u32_e32 v164, s56, v150
	v_lshlrev_b32_e32 v164, 7, v164
	v_lshl_add_u32 v164, v158, 2, v164
	global_store_dwordx2 v164, v[162:163], s[52:53]
	s_add_i32 s46, s46, s60
	s_branch .Lsl_done
.Lsl_meta:
	global_load_dwordx4 v[0:3], v146, s[28:29]
	global_load_dwordx4 v[4:7], v146, s[28:29] offset:16
	global_load_dwordx4 v[8:11], v146, s[28:29] offset:32
	global_load_dwordx4 v[12:15], v146, s[28:29] offset:48
	global_load_dwordx4 v[16:19], v146, s[28:29] offset:128
	global_load_dwordx4 v[20:23], v146, s[28:29] offset:144
	global_load_dwordx4 v[24:27], v146, s[28:29] offset:160
	global_load_dwordx4 v[28:31], v146, s[28:29] offset:176
	global_load_dwordx4 v[32:35], v146, s[28:29] offset:256
	global_load_dwordx4 v[36:39], v146, s[28:29] offset:272
	global_load_dwordx4 v[40:43], v146, s[28:29] offset:288
	global_load_dwordx4 v[44:47], v146, s[28:29] offset:304
	global_load_dwordx4 v[48:51], v146, s[28:29] offset:384
	global_load_dwordx4 v[52:55], v146, s[28:29] offset:400
	global_load_dwordx4 v[56:59], v146, s[28:29] offset:416
	global_load_dwordx4 v[60:63], v146, s[28:29] offset:432
	global_load_dwordx4 v[64:67], v144, s[50:51]
	global_load_dwordx4 v[68:71], v144, s[50:51] offset:16
	global_load_dwordx4 v[72:75], v144, s[50:51] offset:32
	global_load_dwordx4 v[76:79], v144, s[50:51] offset:48
	global_load_dwordx4 v[80:83], v144, s[50:51] offset:128
	global_load_dwordx4 v[84:87], v144, s[50:51] offset:144
	global_load_dwordx4 v[88:91], v144, s[50:51] offset:160
	global_load_dwordx4 v[92:95], v144, s[50:51] offset:176
	global_load_dwordx4 v[96:99], v144, s[50:51] offset:256
	global_load_dwordx4 v[100:103], v144, s[50:51] offset:272
	global_load_dwordx4 v[104:107], v144, s[50:51] offset:288
	global_load_dwordx4 v[108:111], v144, s[50:51] offset:304
	global_load_dwordx4 v[112:115], v144, s[50:51] offset:384
	global_load_dwordx4 v[116:119], v144, s[50:51] offset:400
	global_load_dwordx4 v[120:123], v144, s[50:51] offset:416
	global_load_dwordx4 v[124:127], v144, s[50:51] offset:432
	global_load_dwordx4 v[180:183], v145, s[50:51]
	global_load_dwordx4 v[184:187], v145, s[50:51] offset:16
	global_load_dwordx4 v[188:191], v145, s[50:51] offset:32
	global_load_dwordx4 v[192:195], v145, s[50:51] offset:48
	global_load_dwordx4 v[196:199], v145, s[50:51] offset:128
	global_load_dwordx4 v[200:203], v145, s[50:51] offset:144
	global_load_dwordx4 v[204:207], v145, s[50:51] offset:160
	global_load_dwordx4 v[208:211], v145, s[50:51] offset:176
	global_load_dwordx4 v[212:215], v145, s[50:51] offset:256
	global_load_dwordx4 v[216:219], v145, s[50:51] offset:272
	global_load_dwordx4 v[220:223], v145, s[50:51] offset:288
	global_load_dwordx4 v[224:227], v145, s[50:51] offset:304
	global_load_dwordx4 v[228:231], v145, s[50:51] offset:384
	global_load_dwordx4 v[232:235], v145, s[50:51] offset:400
	global_load_dwordx4 v[236:239], v145, s[50:51] offset:416
	global_load_dwordx4 v[240:243], v145, s[50:51] offset:432
	s_waitcnt vmcnt(28)
	v_mfma_f32_32x32x16_bf16 v[128:143], v[64:67], v[0:3], 0
	v_mfma_f32_32x32x16_bf16 v[128:143], v[68:71], v[4:7], v[128:143]
	v_mfma_f32_32x32x16_bf16 v[128:143], v[72:75], v[8:11], v[128:143]
	v_mfma_f32_32x32x16_bf16 v[128:143], v[76:79], v[12:15], v[128:143]
	s_waitcnt vmcnt(24)
	v_mfma_f32_32x32x16_bf16 v[128:143], v[80:83], v[16:19], v[128:143]
	v_mfma_f32_32x32x16_bf16 v[128:143], v[84:87], v[20:23], v[128:143]
	v_mfma_f32_32x32x16_bf16 v[128:143], v[88:91], v[24:27], v[128:143]
	v_mfma_f32_32x32x16_bf16 v[128:143], v[92:95], v[28:31], v[128:143]
	s_waitcnt vmcnt(20)
	v_mfma_f32_32x32x16_bf16 v[128:143], v[96:99], v[32:35], v[128:143]
	v_mfma_f32_32x32x16_bf16 v[128:143], v[100:103], v[36:39], v[128:143]
	v_mfma_f32_32x32x16_bf16 v[128:143], v[104:107], v[40:43], v[128:143]
	v_mfma_f32_32x32x16_bf16 v[128:143], v[108:111], v[44:47], v[128:143]
	s_waitcnt vmcnt(16)
	v_mfma_f32_32x32x16_bf16 v[128:143], v[112:115], v[48:51], v[128:143]
	v_mfma_f32_32x32x16_bf16 v[128:143], v[116:119], v[52:55], v[128:143]
	v_mfma_f32_32x32x16_bf16 v[128:143], v[120:123], v[56:59], v[128:143]
	v_mfma_f32_32x32x16_bf16 v[128:143], v[124:127], v[60:63], v[128:143]
	global_load_dwordx4 v[64:67], v248, s[50:51]
	global_load_dwordx4 v[68:71], v248, s[50:51] offset:16
	global_load_dwordx4 v[72:75], v248, s[50:51] offset:32
	global_load_dwordx4 v[76:79], v248, s[50:51] offset:48
	global_load_dwordx4 v[80:83], v248, s[50:51] offset:128
	global_load_dwordx4 v[84:87], v248, s[50:51] offset:144
	global_load_dwordx4 v[88:91], v248, s[50:51] offset:160
	global_load_dwordx4 v[92:95], v248, s[50:51] offset:176
	global_load_dwordx4 v[96:99], v248, s[50:51] offset:256
	global_load_dwordx4 v[100:103], v248, s[50:51] offset:272
	global_load_dwordx4 v[104:107], v248, s[50:51] offset:288
	global_load_dwordx4 v[108:111], v248, s[50:51] offset:304
	global_load_dwordx4 v[112:115], v248, s[50:51] offset:384
	global_load_dwordx4 v[116:119], v248, s[50:51] offset:400
	global_load_dwordx4 v[120:123], v248, s[50:51] offset:416
	global_load_dwordx4 v[124:127], v248, s[50:51] offset:432
	s_nop 15
	v_add_u32_e32 v160, s58, v153
	ds_write_b128 v160, v[128:131]
	ds_write_b128 v160, v[132:135] offset:1024
	ds_write_b128 v160, v[136:139] offset:2048
	ds_write_b128 v160, v[140:143] offset:3072
	s_waitcnt lgkmcnt(0)
	s_barrier
	v_add_u32_e32 v161, s58, v156
	ds_read_b64 v[162:163], v161
	ds_read_b64 v[164:165], v161 offset:4096
	ds_read_b64 v[166:167], v161 offset:8192
	ds_read_b64 v[168:169], v161 offset:12288
	ds_read_b64 v[170:171], v161 offset:16384
	ds_read_b64 v[172:173], v161 offset:20480
	ds_read_b64 v[174:175], v161 offset:24576
	ds_read_b64 v[176:177], v161 offset:28672
	s_xor_b32 s58, s58, 0x8000
	s_waitcnt lgkmcnt(0)
	v_add_f32_e32 v162, v162, v164
	v_add_f32_e32 v163, v163, v165
	v_add_f32_e32 v162, v162, v166
	v_add_f32_e32 v163, v163, v167
	v_add_f32_e32 v162, v162, v168
	v_add_f32_e32 v163, v163, v169
	v_add_f32_e32 v162, v162, v170
	v_add_f32_e32 v163, v163, v171
	v_add_f32_e32 v162, v162, v172
	v_add_f32_e32 v163, v163, v173
	v_add_f32_e32 v162, v162, v174
	v_add_f32_e32 v163, v163, v175
	v_add_f32_e32 v162, v162, v176
	v_add_f32_e32 v163, v163, v177
	s_lshr_b32 s56, s46, 3
	s_and_b32 s56, s56, 12
	s_cmp_eq_u32 s56, 12
	s_cbranch_scc0 .Lsl_nogate_m0
	v_mul_f32_e32 v164, 0xbfb8aa3b, v162
	v_mul_f32_e32 v165, 0xbfb8aa3b, v163
	v_exp_f32_e32 v164, v164
	v_exp_f32_e32 v165, v165
	s_nop 0
	v_add_f32_e32 v164, 1.0, v164
	v_add_f32_e32 v165, 1.0, v165
	v_rcp_f32_e32 v164, v164
	v_rcp_f32_e32 v165, v165
	s_nop 0
	v_mul_f32_e32 v162, v162, v164
	v_mul_f32_e32 v163, v163, v165
.Lsl_nogate_m0:
	v_cvt_pk_bf16_f32 v162, v162, v163
	v_add_u32_e32 v164, 0x4000, v150
	v_lshlrev_b32_e32 v164, 14, v164
	s_lshl_b32 s56, s46, 6
	v_lshl_add_u32 v165, v158, 1, s56
	v_add_u32_e32 v164, v164, v165
	global_store_dword v164, v162, s[54:55]
	s_add_i32 s46, s46, s60
	s_waitcnt vmcnt(29)
	v_mfma_f32_32x32x16_bf16 v[128:143], v[180:183], v[0:3], 0
	v_mfma_f32_32x32x16_bf16 v[128:143], v[184:187], v[4:7], v[128:143]
	v_mfma_f32_32x32x16_bf16 v[128:143], v[188:191], v[8:11], v[128:143]
	v_mfma_f32_32x32x16_bf16 v[128:143], v[192:195], v[12:15], v[128:143]
	s_waitcnt vmcnt(25)
	v_mfma_f32_32x32x16_bf16 v[128:143], v[196:199], v[16:19], v[128:143]
	v_mfma_f32_32x32x16_bf16 v[128:143], v[200:203], v[20:23], v[128:143]
	v_mfma_f32_32x32x16_bf16 v[128:143], v[204:207], v[24:27], v[128:143]
	v_mfma_f32_32x32x16_bf16 v[128:143], v[208:211], v[28:31], v[128:143]
	s_waitcnt vmcnt(21)
	v_mfma_f32_32x32x16_bf16 v[128:143], v[212:215], v[32:35], v[128:143]
	v_mfma_f32_32x32x16_bf16 v[128:143], v[216:219], v[36:39], v[128:143]
	v_mfma_f32_32x32x16_bf16 v[128:143], v[220:223], v[40:43], v[128:143]
	v_mfma_f32_32x32x16_bf16 v[128:143], v[224:227], v[44:47], v[128:143]
	s_waitcnt vmcnt(17)
	v_mfma_f32_32x32x16_bf16 v[128:143], v[228:231], v[48:51], v[128:143]
	v_mfma_f32_32x32x16_bf16 v[128:143], v[232:235], v[52:55], v[128:143]
	v_mfma_f32_32x32x16_bf16 v[128:143], v[236:239], v[56:59], v[128:143]
	v_mfma_f32_32x32x16_bf16 v[128:143], v[240:243], v[60:63], v[128:143]
	s_cmp_lt_u32 s57, s61
	s_cbranch_scc0 .Lsl_no3_m
	global_load_dwordx4 v[180:183], v249, s[50:51]
	global_load_dwordx4 v[184:187], v249, s[50:51] offset:16
	global_load_dwordx4 v[188:191], v249, s[50:51] offset:32
	global_load_dwordx4 v[192:195], v249, s[50:51] offset:48
	global_load_dwordx4 v[196:199], v249, s[50:51] offset:128
	global_load_dwordx4 v[200:203], v249, s[50:51] offset:144
	global_load_dwordx4 v[204:207], v249, s[50:51] offset:160
	global_load_dwordx4 v[208:211], v249, s[50:51] offset:176
	global_load_dwordx4 v[212:215], v249, s[50:51] offset:256
	global_load_dwordx4 v[216:219], v249, s[50:51] offset:272
	global_load_dwordx4 v[220:223], v249, s[50:51] offset:288
	global_load_dwordx4 v[224:227], v249, s[50:51] offset:304
	global_load_dwordx4 v[228:231], v249, s[50:51] offset:384
	global_load_dwordx4 v[232:235], v249, s[50:51] offset:400
	global_load_dwordx4 v[236:239], v249, s[50:51] offset:416
	global_load_dwordx4 v[240:243], v249, s[50:51] offset:432
.Lsl_no3_m:
	s_nop 15
	v_add_u32_e32 v160, s58, v153
	ds_write_b128 v160, v[128:131]
	ds_write_b128 v160, v[132:135] offset:1024
	ds_write_b128 v160, v[136:139] offset:2048
	ds_write_b128 v160, v[140:143] offset:3072
	s_waitcnt lgkmcnt(0)
	s_barrier
	v_add_u32_e32 v161, s58, v156
	ds_read_b64 v[162:163], v161
	ds_read_b64 v[164:165], v161 offset:4096
	ds_read_b64 v[166:167], v161 offset:8192
	ds_read_b64 v[168:169], v161 offset:12288
	ds_read_b64 v[170:171], v161 offset:16384
	ds_read_b64 v[172:173], v161 offset:20480
	ds_read_b64 v[174:175], v161 offset:24576
	ds_read_b64 v[176:177], v161 offset:28672
	s_xor_b32 s58, s58, 0x8000
	s_waitcnt lgkmcnt(0)
	v_add_f32_e32 v162, v162, v164
	v_add_f32_e32 v163, v163, v165
	v_add_f32_e32 v162, v162, v166
	v_add_f32_e32 v163, v163, v167
	v_add_f32_e32 v162, v162, v168
	v_add_f32_e32 v163, v163, v169
	v_add_f32_e32 v162, v162, v170
	v_add_f32_e32 v163, v163, v171
	v_add_f32_e32 v162, v162, v172
	v_add_f32_e32 v163, v163, v173
	v_add_f32_e32 v162, v162, v174
	v_add_f32_e32 v163, v163, v175
	v_add_f32_e32 v162, v162, v176
	v_add_f32_e32 v163, v163, v177
	s_lshr_b32 s56, s46, 3
	s_and_b32 s56, s56, 12
	s_cmp_eq_u32 s56, 12
	s_cbranch_scc0 .Lsl_nogate_m1
	v_mul_f32_e32 v164, 0xbfb8aa3b, v162
	v_mul_f32_e32 v165, 0xbfb8aa3b, v163
	v_exp_f32_e32 v164, v164
	v_exp_f32_e32 v165, v165
	s_nop 0
	v_add_f32_e32 v164, 1.0, v164
	v_add_f32_e32 v165, 1.0, v165
	v_rcp_f32_e32 v164, v164
	v_rcp_f32_e32 v165, v165
	s_nop 0
	v_mul_f32_e32 v162, v162, v164
	v_mul_f32_e32 v163, v163, v165
.Lsl_nogate_m1:
	v_cvt_pk_bf16_f32 v162, v162, v163
	v_add_u32_e32 v164, 0x4000, v150
	v_lshlrev_b32_e32 v164, 14, v164
	s_lshl_b32 s56, s46, 6
	v_lshl_add_u32 v165, v158, 1, s56
	v_add_u32_e32 v164, v164, v165
	global_store_dword v164, v162, s[54:55]
	s_add_i32 s46, s46, s60
	s_waitcnt vmcnt(14)
	v_mfma_f32_32x32x16_bf16 v[128:143], v[64:67], v[0:3], 0
	v_mfma_f32_32x32x16_bf16 v[128:143], v[68:71], v[4:7], v[128:143]
	v_mfma_f32_32x32x16_bf16 v[128:143], v[72:75], v[8:11], v[128:143]
	v_mfma_f32_32x32x16_bf16 v[128:143], v[76:79], v[12:15], v[128:143]
	s_waitcnt vmcnt(10)
	v_mfma_f32_32x32x16_bf16 v[128:143], v[80:83], v[16:19], v[128:143]
	v_mfma_f32_32x32x16_bf16 v[128:143], v[84:87], v[20:23], v[128:143]
	v_mfma_f32_32x32x16_bf16 v[128:143], v[88:91], v[24:27], v[128:143]
	v_mfma_f32_32x32x16_bf16 v[128:143], v[92:95], v[28:31], v[128:143]
	s_waitcnt vmcnt(6)
	v_mfma_f32_32x32x16_bf16 v[128:143], v[96:99], v[32:35], v[128:143]
	v_mfma_f32_32x32x16_bf16 v[128:143], v[100:103], v[36:39], v[128:143]
	v_mfma_f32_32x32x16_bf16 v[128:143], v[104:107], v[40:43], v[128:143]
	v_mfma_f32_32x32x16_bf16 v[128:143], v[108:111], v[44:47], v[128:143]
	s_waitcnt vmcnt(2)
	v_mfma_f32_32x32x16_bf16 v[128:143], v[112:115], v[48:51], v[128:143]
	v_mfma_f32_32x32x16_bf16 v[128:143], v[116:119], v[52:55], v[128:143]
	v_mfma_f32_32x32x16_bf16 v[128:143], v[120:123], v[56:59], v[128:143]
	v_mfma_f32_32x32x16_bf16 v[128:143], v[124:127], v[60:63], v[128:143]
	s_nop 15
	v_add_u32_e32 v160, s58, v153
	ds_write_b128 v160, v[128:131]
	ds_write_b128 v160, v[132:135] offset:1024
	ds_write_b128 v160, v[136:139] offset:2048
	ds_write_b128 v160, v[140:143] offset:3072
	s_waitcnt lgkmcnt(0)
	s_barrier
	v_add_u32_e32 v161, s58, v156
	ds_read_b64 v[162:163], v161
	ds_read_b64 v[164:165], v161 offset:4096
	ds_read_b64 v[166:167], v161 offset:8192
	ds_read_b64 v[168:169], v161 offset:12288
	ds_read_b64 v[170:171], v161 offset:16384
	ds_read_b64 v[172:173], v161 offset:20480
	ds_read_b64 v[174:175], v161 offset:24576
	ds_read_b64 v[176:177], v161 offset:28672
	s_xor_b32 s58, s58, 0x8000
	s_waitcnt lgkmcnt(0)
	v_add_f32_e32 v162, v162, v164
	v_add_f32_e32 v163, v163, v165
	v_add_f32_e32 v162, v162, v166
	v_add_f32_e32 v163, v163, v167
	v_add_f32_e32 v162, v162, v168
	v_add_f32_e32 v163, v163, v169
	v_add_f32_e32 v162, v162, v170
	v_add_f32_e32 v163, v163, v171
	v_add_f32_e32 v162, v162, v172
	v_add_f32_e32 v163, v163, v173
	v_add_f32_e32 v162, v162, v174
	v_add_f32_e32 v163, v163, v175
	v_add_f32_e32 v162, v162, v176
	v_add_f32_e32 v163, v163, v177
	s_lshr_b32 s56, s46, 3
	s_and_b32 s56, s56, 12
	s_cmp_eq_u32 s56, 12
	s_cbranch_scc0 .Lsl_nogate_m2
	v_mul_f32_e32 v164, 0xbfb8aa3b, v162
	v_mul_f32_e32 v165, 0xbfb8aa3b, v163
	v_exp_f32_e32 v164, v164
	v_exp_f32_e32 v165, v165
	s_nop 0
	v_add_f32_e32 v164, 1.0, v164
	v_add_f32_e32 v165, 1.0, v165
	v_rcp_f32_e32 v164, v164
	v_rcp_f32_e32 v165, v165
	s_nop 0
	v_mul_f32_e32 v162, v162, v164
	v_mul_f32_e32 v163, v163, v165
.Lsl_nogate_m2:
	v_cvt_pk_bf16_f32 v162, v162, v163
	v_add_u32_e32 v164, 0x4000, v150
	v_lshlrev_b32_e32 v164, 14, v164
	s_lshl_b32 s56, s46, 6
	v_lshl_add_u32 v165, v158, 1, s56
	v_add_u32_e32 v164, v164, v165
	global_store_dword v164, v162, s[54:55]
	s_add_i32 s46, s46, s60
	s_cmp_lt_u32 s57, s61
	s_cbranch_scc0 .Lsl_done
	s_waitcnt vmcnt(14)
	v_mfma_f32_32x32x16_bf16 v[128:143], v[180:183], v[0:3], 0
	v_mfma_f32_32x32x16_bf16 v[128:143], v[184:187], v[4:7], v[128:143]
	v_mfma_f32_32x32x16_bf16 v[128:143], v[188:191], v[8:11], v[128:143]
	v_mfma_f32_32x32x16_bf16 v[128:143], v[192:195], v[12:15], v[128:143]
	s_waitcnt vmcnt(10)
	v_mfma_f32_32x32x16_bf16 v[128:143], v[196:199], v[16:19], v[128:143]
	v_mfma_f32_32x32x16_bf16 v[128:143], v[200:203], v[20:23], v[128:143]
	v_mfma_f32_32x32x16_bf16 v[128:143], v[204:207], v[24:27], v[128:143]
	v_mfma_f32_32x32x16_bf16 v[128:143], v[208:211], v[28:31], v[128:143]
	s_waitcnt vmcnt(6)
	v_mfma_f32_32x32x16_bf16 v[128:143], v[212:215], v[32:35], v[128:143]
	v_mfma_f32_32x32x16_bf16 v[128:143], v[216:219], v[36:39], v[128:143]
	v_mfma_f32_32x32x16_bf16 v[128:143], v[220:223], v[40:43], v[128:143]
	v_mfma_f32_32x32x16_bf16 v[128:143], v[224:227], v[44:47], v[128:143]
	s_waitcnt vmcnt(2)
	v_mfma_f32_32x32x16_bf16 v[128:143], v[228:231], v[48:51], v[128:143]
	v_mfma_f32_32x32x16_bf16 v[128:143], v[232:235], v[52:55], v[128:143]
	v_mfma_f32_32x32x16_bf16 v[128:143], v[236:239], v[56:59], v[128:143]
	v_mfma_f32_32x32x16_bf16 v[128:143], v[240:243], v[60:63], v[128:143]
	s_nop 15
	v_add_u32_e32 v160, s58, v153
	ds_write_b128 v160, v[128:131]
	ds_write_b128 v160, v[132:135] offset:1024
	ds_write_b128 v160, v[136:139] offset:2048
	ds_write_b128 v160, v[140:143] offset:3072
	s_waitcnt lgkmcnt(0)
	s_barrier
	v_add_u32_e32 v161, s58, v156
	ds_read_b64 v[162:163], v161
	ds_read_b64 v[164:165], v161 offset:4096
	ds_read_b64 v[166:167], v161 offset:8192
	ds_read_b64 v[168:169], v161 offset:12288
	ds_read_b64 v[170:171], v161 offset:16384
	ds_read_b64 v[172:173], v161 offset:20480
	ds_read_b64 v[174:175], v161 offset:24576
	ds_read_b64 v[176:177], v161 offset:28672
	s_xor_b32 s58, s58, 0x8000
	s_waitcnt lgkmcnt(0)
	v_add_f32_e32 v162, v162, v164
	v_add_f32_e32 v163, v163, v165
	v_add_f32_e32 v162, v162, v166
	v_add_f32_e32 v163, v163, v167
	v_add_f32_e32 v162, v162, v168
	v_add_f32_e32 v163, v163, v169
	v_add_f32_e32 v162, v162, v170
	v_add_f32_e32 v163, v163, v171
	v_add_f32_e32 v162, v162, v172
	v_add_f32_e32 v163, v163, v173
	v_add_f32_e32 v162, v162, v174
	v_add_f32_e32 v163, v163, v175
	v_add_f32_e32 v162, v162, v176
	v_add_f32_e32 v163, v163, v177
	s_lshr_b32 s56, s46, 3
	s_and_b32 s56, s56, 12
	s_cmp_eq_u32 s56, 12
	s_cbranch_scc0 .Lsl_nogate_m3
	v_mul_f32_e32 v164, 0xbfb8aa3b, v162
	v_mul_f32_e32 v165, 0xbfb8aa3b, v163
	v_exp_f32_e32 v164, v164
	v_exp_f32_e32 v165, v165
	s_nop 0
	v_add_f32_e32 v164, 1.0, v164
	v_add_f32_e32 v165, 1.0, v165
	v_rcp_f32_e32 v164, v164
	v_rcp_f32_e32 v165, v165
	s_nop 0
	v_mul_f32_e32 v162, v162, v164
	v_mul_f32_e32 v163, v163, v165
.Lsl_nogate_m3:
	v_cvt_pk_bf16_f32 v162, v162, v163
	v_add_u32_e32 v164, 0x4000, v150
	v_lshlrev_b32_e32 v164, 14, v164
	s_lshl_b32 s56, s46, 6
	v_lshl_add_u32 v165, v158, 1, s56
	v_add_u32_e32 v164, v164, v165
	global_store_dword v164, v162, s[54:55]
	s_add_i32 s46, s46, s60
	s_branch .Lsl_done
.Lsl_done:
	s_waitcnt vmcnt(0)
	s_barrier
	s_mov_b64 s[0:1], exec
	v_readlane_b32 s4, v246, 0
	v_readlane_b32 s5, v246, 1
	s_and_b64 s[4:5], s[0:1], s[4:5]
	s_xor_b64 s[0:1], s[4:5], s[0:1]
	s_mov_b64 exec, s[4:5]
	s_cbranch_execz .LBB0_290
	s_add_i32 s3, 0, 0x261e0
	v_mov_b32_e32 v0, s3
	s_waitcnt vmcnt(0) expcnt(0) lgkmcnt(0)
	ds_read_b32 v2, v0
	s_add_i32 s3, 0, 0x261e4
	v_mov_b32_e32 v0, s3
	ds_read_b32 v0, v0
	s_waitcnt lgkmcnt(1)
	v_cmp_ne_u32_e32 vcc, 0, v2
	s_cbranch_vccnz .LBB0_253
	s_add_u32 s4, s28, 0x1dc10200
	s_addc_u32 s5, s29, 0
	s_add_u32 s14, s28, 0x1dc10400
	s_addc_u32 s15, s29, 0
	s_add_u32 s42, s28, 0x1dc10500
	s_addc_u32 s43, s29, 0
	s_add_u32 s46, s28, 0x1dc10600
	s_addc_u32 s47, s29, 0
	s_add_u32 s48, s28, 0x1dc10700
	s_addc_u32 s49, s29, 0
	s_add_u32 s50, s28, 0x1dc10800
	s_addc_u32 s51, s29, 0
	s_add_u32 s52, s28, 0x1dc10900
	s_addc_u32 s53, s29, 0
	s_add_u32 s54, s28, 0x1dc10a00
	s_addc_u32 s55, s29, 0
	s_add_u32 s56, s28, 0x1dc10b00
	s_addc_u32 s57, s29, 0
	s_add_u32 s58, s28, 0x1dc10c00
	s_addc_u32 s59, s29, 0
	s_add_u32 s60, s28, 0x1dc10d00
	s_addc_u32 s61, s29, 0
	s_add_u32 s62, s28, 0x1dc10e00
	s_addc_u32 s63, s29, 0
	s_add_u32 s64, s28, 0x1dc10f00
	s_addc_u32 s65, s29, 0
	s_add_u32 s66, s28, 0x1dc11000
	s_addc_u32 s67, s29, 0
	s_add_u32 s68, s28, 0x1dc11100
	s_addc_u32 s69, s29, 0
	s_add_u32 s70, s28, 0x1dc11200
	s_addc_u32 s71, s29, 0
	s_mul_i32 s3, s31, s7
	s_add_u32 s72, s28, 0x1dc11300
	s_mul_i32 s3, s3, s30
	s_addc_u32 s73, s29, 0
	s_mov_b32 s33, 1
	v_mov_b32_e32 v16, 0
	s_branch .LBB0_241
